# ph0: transpose-loop LDS fences no longer drain vmcnt (loads/stores stay in flight); rmsnorm row loop loads the gain vector once before the loop instead of 7 serialised round trips per row
# speedup vs baseline: 1.0300x; 1.0300x over previous
; #define LDS_FENCE() asm volatile("s_waitcnt vmcnt(0) lgkmcnt(0)" ::: "memory")
; __device__ __forceinline__ unsigned pkh(float lo, float hi) { f32v2_t v; v.x = lo; v.y = hi; return __builtin_bit_cast(unsigned, __builtin_convertvector(v, bf16v2_t)); }
; __device__ __forceinline__ void titem_store(const TItem& t, const TRegs& R, float* scrf, int lane) {
;     unsigned* scr = (unsigned*)scrf;
;     const int nblk = (t.N + 63) / 64, kb = t.item / nblk, nb = t.item % nblk, k0 = 64 * kb, n0 = 64 * nb;
;     const int rg = lane >> 4, c4 = lane & 15;
; #pragma unroll
;     for (int i = 0; i < 8; ++i) { unsigned* q = scr + (4 * i + rg) * 66 + 4 * c4;
;         q[0] = pkh(R.v0[i].x, R.v1[i].x); q[1] = pkh(R.v0[i].y, R.v1[i].y); q[2] = pkh(R.v0[i].z, R.v1[i].z); q[3] = pkh(R.v0[i].w, R.v1[i].w); }
;     LDS_FENCE();
;     const int c = lane & 7;
; #pragma unroll
;     for (int j = 0; j < 8; ++j) { const int n = (lane >> 3) + 8 * j; const unsigned* s = scr + (4 * c) * 66 + n;
.LBB0_444:
	s_or_b64 exec, exec, s[8:9]
	s_lshl_b32 s2, s29, 14
	v_readlane_b32 s5, v253, 26
	v_lshrrev_b32_e32 v0, 4, v132
	s_add_i32 s2, s5, s2
	v_mul_u32_u24_e32 v3, 0x108, v0
	v_and_b32_e32 v0, 7, v70
	v_lshl_add_u32 v2, v133, 2, s2
	v_mul_u32_u24_e32 v68, 0x420, v0
	v_lshlrev_b32_e32 v0, 3, v0
	v_lshlrev_b32_e32 v69, 2, v138
	v_add3_u32 v140, s2, v68, v69
	v_or_b32_e32 v141, 8, v138
	v_or_b32_e32 v142, 16, v138
	v_or_b32_e32 v143, 24, v138
	v_or_b32_e32 v144, 32, v138
	v_or_b32_e32 v145, 40, v138
	v_or_b32_e32 v146, 48, v138
	v_or_b32_e32 v147, 56, v138
	v_add_u32_e32 v148, v2, v3
	v_lshlrev_b32_e32 v134, 1, v0
	s_mov_b32 s5, s26
	s_waitcnt vmcnt(0)
	s_branch .LBB0_446

;     __device__ __forceinline__ const float* in(int i) const { return (const float*)(const __attribute__((address_space(1))) float*)get(i); }
; __device__ __forceinline__ TItem decode_item(const PT a, unsigned char* ws, int it) {
;     const int l = it / IT_LAYER; int r = it % IT_LAYER;
;     unsigned char* wl = ws + WS_WT + (size_t)l * LAYER_W; unsigned char* cw = ws + WS_CW + (size_t)l * 4 * MiB;
;     TItem t;
;     if (r < IT_IN) { t.W = a.in(2) + (size_t)l * DM * NIN; t.K = DM; t.N = NIN; t.WT = (bf16*)(wl + WO_IN); t.item = r; t.pitch = t.K; return t; } r -= IT_IN;
;     if (r < IT_A) { t.W = a.in(11) + (size_t)l * 512 * DM; t.K = 512; t.N = DM; t.WT = (bf16*)(wl + WO_A); t.item = r; t.pitch = 2560; return t; } r -= IT_A;
;     if (r < IT_B) { t.W = a.in(12) + (size_t)l * 1024 * DM; t.K = 1024; t.N = DM; t.WT = (bf16*)(wl + WO_A) + 512; t.item = r; t.pitch = 2560; return t; } r -= IT_B;
;     if (r < IT_C) { t.W = a.in(13) + (size_t)l * 1024 * DM; t.K = 1024; t.N = DM; t.WT = (bf16*)(wl + WO_A) + 1536; t.item = r; t.pitch = 2560; return t; } r -= IT_C;
;     if (r < IT_OUT) { t.W = a.in(14) + (size_t)l * DM * DM; t.K = DM; t.N = DM; t.WT = (bf16*)(wl + WO_OUT); t.item = r; t.pitch = t.K; return t; } r -= IT_OUT;
;     if (r < IT_UP) { t.W = a.in(19) + (size_t)l * DM * DFF; t.K = DM; t.N = DFF; t.WT = (bf16*)(wl + WO_UP); t.item = r; t.pitch = t.K; return t; } r -= IT_UP;
;     if (r < IT_DOWN) { t.W = a.in(20) + (size_t)l * DFF * DM; t.K = DFF; t.N = DM; t.WT = (bf16*)(wl + WO_DOWN); t.item = r; t.pitch = t.K; return t; } r -= IT_DOWN;
; __device__ __forceinline__ void phase_prologue(const PT a, float* ldsf, int lane, int wave, int gw, int ngw) {
;     ...
;         for (;;) {
;             const int nx = it + ngw; const bool more = nx < NIT;
;             TItem nxt = cur; TRegs R2 = R;
;             if (more) { nxt = decode_item(a, ws, nx); titem_load(nxt, R2, lane); }
;             titem_store(cur, R, scr, lane);
;             if (!more) break;
;             cur = nxt; R = R2; it = nx;
.LBB0_446:
	s_add_i32 s36, s5, s84
	s_cmp_lt_i32 s36, 0x9150
	s_cselect_b64 s[8:9], -1, 0
	s_cmp_gt_i32 s36, 0x914f
	s_cselect_b64 s[6:7], -1, 0
	v_mov_b64_e32 v[70:71], v[10:11]
	v_mov_b64_e32 v[78:79], v[18:19]
	v_mov_b64_e32 v[86:87], v[26:27]
	v_mov_b64_e32 v[94:95], v[34:35]
	v_mov_b64_e32 v[102:103], v[42:43]
	v_mov_b64_e32 v[110:111], v[50:51]
	v_mov_b64_e32 v[118:119], v[58:59]
	v_mov_b64_e32 v[126:127], v[66:67]
	v_mov_b64_e32 v[74:75], v[6:7]
	v_mov_b64_e32 v[82:83], v[14:15]
	v_mov_b64_e32 v[90:91], v[22:23]
	v_mov_b64_e32 v[98:99], v[30:31]
	v_mov_b64_e32 v[106:107], v[38:39]
	v_mov_b64_e32 v[114:115], v[46:47]
	v_mov_b64_e32 v[122:123], v[54:55]
	v_mov_b64_e32 v[130:131], v[62:63]
	s_and_b64 vcc, exec, s[6:7]
	v_mov_b64_e32 v[68:69], v[8:9]
	v_mov_b64_e32 v[76:77], v[16:17]
	v_mov_b64_e32 v[84:85], v[24:25]
	v_mov_b64_e32 v[92:93], v[32:33]
	v_mov_b64_e32 v[100:101], v[40:41]
	v_mov_b64_e32 v[108:109], v[48:49]
	v_mov_b64_e32 v[116:117], v[56:57]
	v_mov_b64_e32 v[124:125], v[64:65]
	v_mov_b64_e32 v[72:73], v[4:5]
	v_mov_b64_e32 v[80:81], v[12:13]
	v_mov_b64_e32 v[88:89], v[20:21]
	v_mov_b64_e32 v[96:97], v[28:29]
	v_mov_b64_e32 v[104:105], v[36:37]
	v_mov_b64_e32 v[112:113], v[44:45]
	v_mov_b64_e32 v[120:121], v[52:53]
	v_mov_b64_e32 v[128:129], v[60:61]
	s_mov_b64 s[10:11], s[0:1]
	s_mov_b32 s90, s4
	s_mov_b32 s37, s34
	s_mov_b32 s24, s35
	s_cbranch_vccnz .LBB0_503
	s_mul_hi_i32 s2, s36, 0xe1800e19
	s_add_i32 s2, s2, s36
	s_lshr_b32 s10, s2, 31
	s_ashr_i32 s2, s2, 14
	s_add_i32 s16, s2, s10
	s_mul_i32 s2, s16, 0x48a8
	s_sub_i32 s38, s36, s2
	s_ashr_i32 s17, s16, 31
	s_mul_i32 s10, s16, 0x9000000
	s_mul_hi_i32 s2, s16, 0x9000000
	s_add_u32 s12, s28, s10
	s_addc_u32 s13, s27, s2
	s_cmpk_gt_i32 s38, 0x1e9f
	s_mov_b64 s[18:19], -1
	s_cbranch_scc0 .LBB0_484
	s_lshl_b64 s[18:19], s[16:17], 22
	s_cmpk_gt_u32 s38, 0x1f9f
	s_mov_b64 s[20:21], -1
	s_cbranch_scc0 .LBB0_481
	s_cmpk_gt_u32 s38, 0x219f
	s_cbranch_scc0 .LBB0_478
	s_cmpk_gt_u32 s38, 0x239f
	s_cbranch_scc0 .LBB0_475
	s_cmpk_gt_u32 s38, 0x279f
	s_cbranch_scc0 .LBB0_472
	s_cmpk_gt_u32 s38, 0x379f
	s_cbranch_scc0 .LBB0_469
	s_cmpk_gt_u32 s38, 0x479f
	s_cbranch_scc0 .LBB0_466
	s_add_u32 s20, s30, s18
	s_addc_u32 s21, s31, s19
	s_cmpk_gt_u32 s38, 0x481f
	s_mov_b64 s[22:23], -1
	s_cbranch_scc0 .LBB0_463
	s_cmpk_gt_u32 s38, 0x489f
	s_cbranch_scc0 .LBB0_461
	s_lshl_b64 s[22:23], s[16:17], 16
	s_cmpk_gt_u32 s38, 0x48a3
	s_mov_b64 s[24:25], -1
	s_cbranch_scc0 .LBB0_458
	v_mov_b32_e32 v0, s73
	ds_read_b64 v[2:3], v0 offset:64
	s_add_i32 s37, s38, 0xffffb75c
	s_mov_b64 s[24:25], 0
	s_waitcnt lgkmcnt(0)
	v_readfirstlane_b32 s10, v2
	v_readfirstlane_b32 s2, v3
	s_add_u32 s14, s10, s22
	s_addc_u32 s15, s2, s23
	s_add_u32 s10, s20, 0x210000
	s_addc_u32 s11, s21, 0

; #define LDS_FENCE() asm volatile("s_waitcnt vmcnt(0) lgkmcnt(0)" ::: "memory")
; __device__ __forceinline__ unsigned pkh(float lo, float hi) { f32v2_t v; v.x = lo; v.y = hi; return __builtin_bit_cast(unsigned, __builtin_convertvector(v, bf16v2_t)); }
; __device__ __forceinline__ void titem_store(const TItem& t, const TRegs& R, float* scrf, int lane) {
;     unsigned* scr = (unsigned*)scrf;
;     const int nblk = (t.N + 63) / 64, kb = t.item / nblk, nb = t.item % nblk, k0 = 64 * kb, n0 = 64 * nb;
;     const int rg = lane >> 4, c4 = lane & 15;
; #pragma unroll
;     for (int i = 0; i < 8; ++i) { unsigned* q = scr + (4 * i + rg) * 66 + 4 * c4;
;         q[0] = pkh(R.v0[i].x, R.v1[i].x); q[1] = pkh(R.v0[i].y, R.v1[i].y); q[2] = pkh(R.v0[i].z, R.v1[i].z); q[3] = pkh(R.v0[i].w, R.v1[i].w); }
;     LDS_FENCE();
;     const int c = lane & 7;
; #pragma unroll
;     for (int j = 0; j < 8; ++j) { const int n = (lane >> 3) + 8 * j; const unsigned* s = scr + (4 * c) * 66 + n;
;         u32x4 o; o.x = s[0]; o.y = s[66]; o.z = s[132]; o.w = s[198];
;         *(u32x4*)(t.WT + (size_t)(n0 + n) * t.pitch + k0 + 8 * c) = o; }
;     LDS_FENCE();
.LBB0_503:
	s_add_i32 s12, s4, 63
	s_lshr_b32 s13, s12, 6
	s_abs_i32 s15, s13
	v_cvt_f32_u32_e32 v0, s15
	v_cvt_pk_bf16_f32 v2, v9, v5
	s_sub_i32 s16, 0, s15
	v_cvt_pk_bf16_f32 v3, v17, v13
	v_rcp_iflag_f32_e32 v0, v0
	s_abs_i32 s14, s34
	s_xor_b32 s12, s34, s13
	s_ashr_i32 s12, s12, 31
	v_mul_f32_e32 v0, 0x4f7ffffe, v0
	v_cvt_u32_f32_e32 v0, v0
	v_mov_b32_e32 v135, v1
	v_readfirstlane_b32 s17, v0
	v_cvt_pk_bf16_f32 v0, v8, v4
	ds_write2_b32 v148, v0, v2 offset1:1
	v_cvt_pk_bf16_f32 v0, v10, v6
	v_cvt_pk_bf16_f32 v2, v11, v7
	ds_write2_b32 v148, v0, v2 offset0:2 offset1:3
	v_cvt_pk_bf16_f32 v0, v16, v12
	v_add_u32_e32 v2, 0x420, v148
	s_mul_i32 s16, s16, s17
	ds_write2_b32 v2, v0, v3 offset1:1
	v_cvt_pk_bf16_f32 v0, v18, v14
	v_add_u32_e32 v2, 0x428, v148
	v_cvt_pk_bf16_f32 v3, v19, v15
	s_mul_hi_u32 s16, s17, s16
	ds_write2_b32 v2, v0, v3 offset1:1
	v_cvt_pk_bf16_f32 v0, v24, v20
	v_add_u32_e32 v2, 0x840, v148
	v_cvt_pk_bf16_f32 v3, v25, v21
	s_add_i32 s17, s17, s16
	ds_write2_b32 v2, v0, v3 offset1:1
	v_cvt_pk_bf16_f32 v0, v26, v22
	v_add_u32_e32 v2, 0x848, v148
	v_cvt_pk_bf16_f32 v3, v27, v23
	s_mul_hi_u32 s16, s14, s17
	ds_write2_b32 v2, v0, v3 offset1:1
	v_cvt_pk_bf16_f32 v0, v32, v28
	v_add_u32_e32 v2, 0xc60, v148
	v_cvt_pk_bf16_f32 v3, v33, v29
	s_mul_i32 s17, s16, s15
	ds_write2_b32 v2, v0, v3 offset1:1
	v_cvt_pk_bf16_f32 v0, v34, v30
	v_add_u32_e32 v2, 0xc68, v148
	v_cvt_pk_bf16_f32 v3, v35, v31
	s_sub_i32 s14, s14, s17
	ds_write2_b32 v2, v0, v3 offset1:1
	v_cvt_pk_bf16_f32 v0, v40, v36
	v_add_u32_e32 v2, 0x1080, v148
	v_cvt_pk_bf16_f32 v3, v41, v37
	s_add_i32 s17, s16, 1
	s_sub_i32 s18, s14, s15
	ds_write2_b32 v2, v0, v3 offset1:1
	v_cvt_pk_bf16_f32 v0, v42, v38
	v_add_u32_e32 v2, 0x1088, v148
	v_cvt_pk_bf16_f32 v3, v43, v39
	s_cmp_ge_u32 s14, s15
	ds_write2_b32 v2, v0, v3 offset1:1
	v_cvt_pk_bf16_f32 v0, v48, v44
	v_add_u32_e32 v2, 0x14a0, v148
	v_cvt_pk_bf16_f32 v3, v49, v45
	s_cselect_b32 s16, s17, s16
	ds_write2_b32 v2, v0, v3 offset1:1
	v_cvt_pk_bf16_f32 v0, v50, v46
	v_add_u32_e32 v2, 0x14a8, v148
	v_cvt_pk_bf16_f32 v3, v51, v47
	s_cselect_b32 s14, s18, s14
	s_add_i32 s17, s16, 1
	ds_write2_b32 v2, v0, v3 offset1:1
	v_cvt_pk_bf16_f32 v0, v56, v52
	v_add_u32_e32 v2, 0x18c0, v148
	v_cvt_pk_bf16_f32 v3, v57, v53
	s_cmp_ge_u32 s14, s15
	ds_write2_b32 v2, v0, v3 offset1:1
	v_cvt_pk_bf16_f32 v0, v58, v54
	v_add_u32_e32 v2, 0x18c8, v148
	v_cvt_pk_bf16_f32 v3, v59, v55
	s_cselect_b32 s14, s17, s16
	ds_write2_b32 v2, v0, v3 offset1:1
	v_cvt_pk_bf16_f32 v0, v64, v60
	v_add_u32_e32 v2, 0x1ce0, v148
	v_cvt_pk_bf16_f32 v3, v65, v61
	s_xor_b32 s14, s14, s12
	ds_write2_b32 v2, v0, v3 offset1:1
	v_cvt_pk_bf16_f32 v0, v66, v62
	v_add_u32_e32 v2, 0x1ce8, v148
	v_cvt_pk_bf16_f32 v3, v67, v63
	s_sub_i32 s14, s14, s12
	ds_write2_b32 v2, v0, v3 offset1:1
	s_lshl_b32 s12, s14, 6
	s_mul_i32 s14, s14, s13
	s_waitcnt lgkmcnt(0)
	s_sub_i32 s13, s34, s14
	ds_read2_b32 v[150:151], v140 offset0:66 offset1:74
	ds_read2_b32 v[2:3], v140 offset0:132 offset1:140
	ds_read2_b32 v[152:153], v140 offset0:198 offset1:206
	ds_read2_b32 v[136:137], v140 offset1:8
	s_lshl_b32 s14, s13, 6
	v_or_b32_e32 v0, s14, v138
	v_mad_u64_u32 v[158:159], s[16:17], v0, s35, 0
	s_ashr_i32 s15, s14, 31
	v_or_b32_e32 v0, s14, v141
	s_waitcnt lgkmcnt(2)
	v_mov_b32_e32 v156, v2
	s_waitcnt lgkmcnt(1)
	v_mov_b32_e32 v157, v152
	s_mul_i32 s18, s15, s35
	v_mov_b32_e32 v152, v3
	v_mad_u64_u32 v[2:3], s[16:17], v0, s35, 0
	s_ashr_i32 s13, s12, 31
	v_add_u32_e32 v159, s18, v159
	v_add_u32_e32 v3, s18, v3
	v_lshl_add_u64 v[158:159], v[158:159], 1, s[0:1]
	s_lshl_b64 s[12:13], s[12:13], 1
	v_lshl_add_u64 v[2:3], v[2:3], 1, s[0:1]
	v_lshl_add_u64 v[158:159], v[158:159], 0, s[12:13]
	v_lshl_add_u64 v[2:3], v[2:3], 0, s[12:13]
	s_waitcnt lgkmcnt(0)
	v_mov_b32_e32 v154, v136
	v_mov_b32_e32 v155, v150
	v_lshl_add_u64 v[158:159], v[158:159], 0, v[134:135]
	v_mov_b32_e32 v150, v137
	v_lshl_add_u64 v[2:3], v[2:3], 0, v[134:135]
	global_store_dwordx4 v[158:159], v[154:157], off
	global_store_dwordx4 v[2:3], v[150:153], off
	ds_read2_b32 v[2:3], v140 offset0:16 offset1:24
	ds_read2_b32 v[150:151], v140 offset0:82 offset1:90
	ds_read2_b32 v[136:137], v140 offset0:148 offset1:156
	ds_read2_b32 v[152:153], v140 offset0:214 offset1:222
	v_or_b32_e32 v0, s14, v142
	v_mad_u64_u32 v[158:159], s[16:17], v0, s35, 0
	v_or_b32_e32 v0, s14, v143
	s_waitcnt lgkmcnt(3)
; #define LDS_FENCE() asm volatile("s_waitcnt vmcnt(0) lgkmcnt(0)" ::: "memory")
; __device__ __forceinline__ void titem_store(const TItem& t, const TRegs& R, float* scrf, int lane) {
;     ...
;     for (int j = 0; j < 8; ++j) { const int n = (lane >> 3) + 8 * j; const unsigned* s = scr + (4 * c) * 66 + n;
;         u32x4 o; o.x = s[0]; o.y = s[66]; o.z = s[132]; o.w = s[198];
;         *(u32x4*)(t.WT + (size_t)(n0 + n) * t.pitch + k0 + 8 * c) = o; }
;     LDS_FENCE();
; __device__ __forceinline__ void phase_prologue(const PT a, float* ldsf, int lane, int wave, int gw, int ngw) {
;     ...
;             TItem nxt = cur; TRegs R2 = R;
;             if (more) { nxt = decode_item(a, ws, nx); titem_load(nxt, R2, lane); }
;             titem_store(cur, R, scr, lane);
;             if (!more) break;
;             cur = nxt; R = R2; it = nx;
	v_mov_b32_e32 v154, v2
	s_waitcnt lgkmcnt(2)
	v_mov_b32_e32 v155, v150
	v_mov_b32_e32 v150, v3
	v_mad_u64_u32 v[2:3], s[16:17], v0, s35, 0
	v_add_u32_e32 v159, s18, v159
	v_add_u32_e32 v3, s18, v3
	v_lshl_add_u64 v[158:159], v[158:159], 1, s[0:1]
	v_lshl_add_u64 v[2:3], v[2:3], 1, s[0:1]
	v_lshl_add_u64 v[158:159], v[158:159], 0, s[12:13]
	v_lshl_add_u64 v[2:3], v[2:3], 0, s[12:13]
	s_waitcnt lgkmcnt(1)
	v_mov_b32_e32 v156, v136
	s_waitcnt lgkmcnt(0)
	v_mov_b32_e32 v157, v152
	v_lshl_add_u64 v[158:159], v[158:159], 0, v[134:135]
	v_mov_b32_e32 v152, v137
	v_lshl_add_u64 v[2:3], v[2:3], 0, v[134:135]
	global_store_dwordx4 v[158:159], v[154:157], off
	global_store_dwordx4 v[2:3], v[150:153], off
	ds_read2_b32 v[2:3], v140 offset0:32 offset1:40
	ds_read2_b32 v[150:151], v140 offset0:98 offset1:106
	ds_read2_b32 v[136:137], v140 offset0:164 offset1:172
	ds_read2_b32 v[152:153], v140 offset0:230 offset1:238
	v_or_b32_e32 v0, s14, v144
	v_mad_u64_u32 v[158:159], s[16:17], v0, s35, 0
	v_or_b32_e32 v0, s14, v145
	s_waitcnt lgkmcnt(3)
	v_mov_b32_e32 v154, v2
	s_waitcnt lgkmcnt(2)
	v_mov_b32_e32 v155, v150
	v_mov_b32_e32 v150, v3
	v_mad_u64_u32 v[2:3], s[16:17], v0, s35, 0
	v_add_u32_e32 v159, s18, v159
	v_add_u32_e32 v3, s18, v3
	v_lshl_add_u64 v[158:159], v[158:159], 1, s[0:1]
	v_lshl_add_u64 v[2:3], v[2:3], 1, s[0:1]
	v_lshl_add_u64 v[158:159], v[158:159], 0, s[12:13]
	v_lshl_add_u64 v[2:3], v[2:3], 0, s[12:13]
	s_waitcnt lgkmcnt(1)
	v_mov_b32_e32 v156, v136
	s_waitcnt lgkmcnt(0)
	v_mov_b32_e32 v157, v152
	v_lshl_add_u64 v[158:159], v[158:159], 0, v[134:135]
	v_mov_b32_e32 v152, v137
	v_lshl_add_u64 v[2:3], v[2:3], 0, v[134:135]
	global_store_dwordx4 v[158:159], v[154:157], off
	global_store_dwordx4 v[2:3], v[150:153], off
	ds_read2_b32 v[2:3], v140 offset0:48 offset1:56
	ds_read2_b32 v[150:151], v140 offset0:114 offset1:122
	ds_read2_b32 v[136:137], v140 offset0:180 offset1:188
	ds_read2_b32 v[152:153], v140 offset0:246 offset1:254
	v_or_b32_e32 v0, s14, v146
	v_mad_u64_u32 v[158:159], s[16:17], v0, s35, 0
	v_or_b32_e32 v0, s14, v147
	s_waitcnt lgkmcnt(3)
	v_mov_b32_e32 v154, v2
	s_waitcnt lgkmcnt(2)
	v_mov_b32_e32 v155, v150
	v_mov_b32_e32 v150, v3
	v_mad_u64_u32 v[2:3], s[14:15], v0, s35, 0
	v_add_u32_e32 v159, s18, v159
	v_add_u32_e32 v3, s18, v3
	v_lshl_add_u64 v[158:159], v[158:159], 1, s[0:1]
	v_lshl_add_u64 v[2:3], v[2:3], 1, s[0:1]
	v_lshl_add_u64 v[158:159], v[158:159], 0, s[12:13]
	v_lshl_add_u64 v[2:3], v[2:3], 0, s[12:13]
	s_waitcnt lgkmcnt(1)
	v_mov_b32_e32 v156, v136
	s_waitcnt lgkmcnt(0)
	v_mov_b32_e32 v157, v152
	v_lshl_add_u64 v[158:159], v[158:159], 0, v[134:135]
	v_mov_b32_e32 v152, v137
	v_lshl_add_u64 v[2:3], v[2:3], 0, v[134:135]
	global_store_dwordx4 v[158:159], v[154:157], off
	global_store_dwordx4 v[2:3], v[150:153], off
	s_waitcnt lgkmcnt(0)
	s_andn2_b64 vcc, exec, s[8:9]
	s_cbranch_vccnz .LBB0_445
	s_waitcnt vmcnt(8)
	v_mov_b64_e32 v[60:61], v[128:129]
	v_mov_b64_e32 v[52:53], v[120:121]
	v_mov_b64_e32 v[44:45], v[112:113]
	v_mov_b64_e32 v[36:37], v[104:105]
	v_mov_b64_e32 v[28:29], v[96:97]
	v_mov_b64_e32 v[20:21], v[88:89]
	v_mov_b64_e32 v[12:13], v[80:81]
	v_mov_b64_e32 v[4:5], v[72:73]
	v_mov_b64_e32 v[64:65], v[124:125]
	v_mov_b64_e32 v[56:57], v[116:117]
	v_mov_b64_e32 v[48:49], v[108:109]
	v_mov_b64_e32 v[40:41], v[100:101]
	v_mov_b64_e32 v[32:33], v[92:93]
	v_mov_b64_e32 v[24:25], v[84:85]
	v_mov_b64_e32 v[16:17], v[76:77]
	v_mov_b64_e32 v[8:9], v[68:69]
	s_mov_b32 s35, s24
	s_mov_b32 s34, s37
	s_mov_b32 s4, s90
	s_mov_b64 s[0:1], s[10:11]
	v_mov_b64_e32 v[62:63], v[130:131]
	v_mov_b64_e32 v[54:55], v[122:123]
	v_mov_b64_e32 v[46:47], v[114:115]
	v_mov_b64_e32 v[38:39], v[106:107]
	v_mov_b64_e32 v[30:31], v[98:99]
	v_mov_b64_e32 v[22:23], v[90:91]
	v_mov_b64_e32 v[14:15], v[82:83]
	v_mov_b64_e32 v[6:7], v[74:75]
	v_mov_b64_e32 v[66:67], v[126:127]
	v_mov_b64_e32 v[58:59], v[118:119]
	v_mov_b64_e32 v[50:51], v[110:111]
	v_mov_b64_e32 v[42:43], v[102:103]
	v_mov_b64_e32 v[34:35], v[94:95]
	v_mov_b64_e32 v[26:27], v[86:87]
	v_mov_b64_e32 v[18:19], v[78:79]
	v_mov_b64_e32 v[10:11], v[70:71]
	s_mov_b32 s5, s36
	s_branch .LBB0_445

;     __device__ __forceinline__ const float* in(int i) const { return (const float*)(const __attribute__((address_space(1))) float*)get(i); }
; __device__ __forceinline__ unsigned pk2(float lo, float hi) { return f2bf(lo) | (f2bf(hi) << 16); }
; __device__ __forceinline__ void rms_row_to_bf16(const float* xrow, const float* gain, bf16* orow, int lane) {
;     const f32x4* xr = (const f32x4*)xrow + lane; const f32x4* gr = (const f32x4*)gain + lane;
;     f32x4 v[8]; float s = 0.f;
; #pragma unroll
;     for (int j = 0; j < 8; ++j) { v[j] = xr[64 * j]; s += (v[j].x * v[j].x + v[j].y * v[j].y) + (v[j].z * v[j].z + v[j].w * v[j].w); }
;     const float r = 1.0f / sqrtf(wave_sum(s) * (1.0f / DM) + 1e-6f);
;     u32x2* o8 = (u32x2*)orow + lane;
; #pragma unroll
;     for (int j = 0; j < 8; ++j) { const f32x4 g = gr[64 * j]; u32x2 w; w.x = pk2(v[j].x * r * g.x, v[j].y * r * g.y); w.y = pk2(v[j].z * r * g.z, v[j].w * r * g.w); o8[64 * j] = w; }
; __device__ __forceinline__ void phase_prologue(const PT a, float* ldsf, int lane, int wave, int gw, int ngw) {
;     ...
;     for (int m = gw; m < M; m += ngw) rms_row_to_bf16(a.in(0) + (size_t)m * DM, a.in(15), (bf16*)(ws + WS_H) + (size_t)m * DM, lane);
.LBB0_511:
	s_or_b64 exec, exec, s[0:1]
	s_cmpk_gt_i32 s26, 0x1fff
	s_cbranch_scc1 .LBB0_514
	v_and_b32_e32 v0, 64, v220
	v_add_u32_e32 v0, 64, v0
	v_xor_b32_e32 v2, 32, v220
	v_cmp_lt_i32_e32 vcc, v2, v0
	s_ashr_i32 s1, s29, 31
	v_readlane_b32 s0, v253, 9
	v_cndmask_b32_e32 v2, v220, v2, vcc
	v_lshlrev_b32_e32 v48, 2, v2
	v_xor_b32_e32 v2, 16, v220
	v_cmp_lt_i32_e32 vcc, v2, v0
	s_add_u32 s0, s0, s29
	v_readlane_b32 s2, v253, 10
	v_cndmask_b32_e32 v2, v220, v2, vcc
	v_lshlrev_b32_e32 v49, 2, v2
	v_xor_b32_e32 v2, 8, v220
	v_cmp_lt_i32_e32 vcc, v2, v0
	s_addc_u32 s1, s2, s1
	s_lshl_b64 s[4:5], s[0:1], 13
	v_cndmask_b32_e32 v2, v220, v2, vcc
	v_lshlrev_b32_e32 v50, 2, v2
	v_xor_b32_e32 v2, 4, v220
	v_cmp_lt_i32_e32 vcc, v2, v0
	s_lshl_b64 s[0:1], s[0:1], 12
	s_add_u32 s0, s28, s0
	v_cndmask_b32_e32 v2, v220, v2, vcc
	v_lshlrev_b32_e32 v51, 2, v2
	v_xor_b32_e32 v2, 2, v220
	v_cmp_lt_i32_e32 vcc, v2, v0
	s_addc_u32 s1, s27, s1
	v_readlane_b32 s6, v253, 15
	v_cndmask_b32_e32 v2, v220, v2, vcc
	v_lshlrev_b32_e32 v52, 2, v2
	v_xor_b32_e32 v2, 1, v220
	v_cmp_lt_i32_e32 vcc, v2, v0
	v_mov_b32_e32 v43, s5
	v_readlane_b32 s7, v253, 16
	v_cndmask_b32_e32 v0, v220, v2, vcc
	v_lshlrev_b32_e32 v53, 2, v0
	v_mov_b32_e32 v0, s73
	ds_read2_b64 v[2:5], v0 offset1:15
	v_lshl_or_b32 v0, v132, 4, s4
	v_or_b32_e32 v42, 0x1c00, v0
	v_lshlrev_b32_e32 v0, 3, v132
	v_lshl_add_u64 v[6:7], s[0:1], 0, v[0:1]
	s_mov_b64 s[0:1], 0x12000800
	v_lshl_add_u64 v[44:45], v[6:7], 0, s[0:1]
	v_lshlrev_b32_e32 v0, 4, v132
	s_waitcnt lgkmcnt(0)
	v_readfirstlane_b32 s4, v4
	v_readfirstlane_b32 s5, v5
	s_nop 4
	global_load_dwordx4 v[84:87], v0, s[4:5] offset:1024
	global_load_dwordx4 v[88:91], v0, s[4:5] offset:2048
	global_load_dwordx4 v[92:95], v0, s[4:5] offset:3072
	s_add_u32 s0, s4, 0x1000
	s_addc_u32 s1, s5, 0
	global_load_dwordx4 v[96:99], v0, s[0:1]
	global_load_dwordx4 v[100:103], v0, s[0:1] offset:1024
	global_load_dwordx4 v[104:107], v0, s[0:1] offset:2048
	global_load_dwordx4 v[108:111], v0, s[0:1] offset:3072
.LBB0_513:
	s_waitcnt lgkmcnt(0)
	v_readfirstlane_b32 s1, v3
	v_readfirstlane_b32 s0, v2
	v_readfirstlane_b32 s5, v5
	v_readfirstlane_b32 s4, v4
	v_lshl_add_u64 v[6:7], s[0:1], 0, v[42:43]
	v_add_co_u32_e32 v8, vcc, 0xfffff000, v6
	s_add_i32 s26, s26, s84
	s_nop 0
	v_addc_co_u32_e32 v9, vcc, -1, v7, vcc
	global_load_dwordx4 v[34:37], v0, s[4:5]
	global_load_dwordx4 v[18:21], v[6:7], off offset:-3072
	global_load_dwordx4 v[22:25], v[6:7], off offset:-4096
	global_load_dwordx4 v[14:17], v[6:7], off offset:-2048
	global_load_dwordx4 v[10:13], v[6:7], off offset:-1024
	global_load_dwordx4 v[38:41], v[8:9], off offset:-3072
	global_load_dwordx4 v[30:33], v[8:9], off offset:-2048
	global_load_dwordx4 v[26:29], v[8:9], off offset:-1024
	s_nop 0
	global_load_dwordx4 v[6:9], v[6:7], off
	v_lshl_add_u64 v[42:43], v[42:43], 0, s[56:57]
	s_cmpk_gt_i32 s26, 0x1fff
	s_waitcnt vmcnt(7)
	v_mul_f32_e32 v78, v20, v20
	s_waitcnt vmcnt(6)
	v_mul_f32_e32 v54, v25, v25
	v_mov_b32_e32 v46, v34
	v_mul_f32_e32 v34, v23, v23
	s_waitcnt vmcnt(5)
	v_pk_mul_f32 v[56:57], v[16:17], v[16:17]
	v_pk_mul_f32 v[58:59], v[14:15], v[14:15]
	v_mov_b32_e32 v47, v36
	v_mov_b32_e32 v36, v35
	s_waitcnt vmcnt(4)
	v_mul_f32_e32 v60, v11, v11
	v_mul_f32_e32 v62, v13, v13
	v_pk_fma_f32 v[64:65], v[22:23], v[22:23], v[34:35] op_sel_hi:[1,1,0]
	v_pk_mov_b32 v[34:35], v[58:59], v[56:57] op_sel:[1,0]
	v_mov_b32_e32 v59, v57
	s_waitcnt vmcnt(3)
	v_mov_b32_e32 v66, v39
	s_waitcnt vmcnt(2)
	v_mov_b32_e32 v67, v31
	v_mov_b32_e32 v70, v41
	v_mov_b32_e32 v71, v33
	v_mul_f32_e32 v79, v21, v21
	v_pk_fma_f32 v[54:55], v[24:25], v[24:25], v[54:55] op_sel_hi:[1,1,0]
	v_pk_fma_f32 v[56:57], v[10:11], v[10:11], v[60:61] op_sel_hi:[1,1,0]
	v_pk_fma_f32 v[60:61], v[12:13], v[12:13], v[62:63] op_sel_hi:[1,1,0]
	v_mov_b32_e32 v62, v38
	v_mov_b32_e32 v63, v30
	v_mov_b32_e32 v68, v40
	v_mov_b32_e32 v69, v32
	s_waitcnt vmcnt(1)
	v_pk_mul_f32 v[72:73], v[28:29], v[28:29]
	v_pk_mul_f32 v[74:75], v[26:27], v[26:27]
	v_pk_add_f32 v[58:59], v[34:35], v[58:59]
	v_mov_b32_e32 v34, v38
	v_mov_b32_e32 v35, v40
	v_mov_b32_e32 v40, v39
	v_mov_b32_e32 v38, v30
	v_mov_b32_e32 v39, v32
	v_mov_b32_e32 v32, v31
	v_pk_mul_f32 v[30:31], v[66:67], v[66:67]
	v_pk_mul_f32 v[66:67], v[70:71], v[70:71]
	v_mov_b32_e32 v65, v78
	v_mov_b32_e32 v55, v79
	v_pk_mov_b32 v[70:71], v[74:75], v[72:73] op_sel:[1,0]
	v_mov_b32_e32 v75, v73
	v_pk_fma_f32 v[30:31], v[62:63], v[62:63], v[30:31]
	v_pk_fma_f32 v[62:63], v[68:69], v[68:69], v[66:67]
	s_waitcnt vmcnt(0)
	v_mul_f32_e32 v57, v8, v8
	v_mul_f32_e32 v61, v9, v9
	v_pk_add_f32 v[54:55], v[64:65], v[54:55]
	v_pk_add_f32 v[64:65], v[70:71], v[74:75]
	v_pk_add_f32 v[30:31], v[30:31], v[62:63]
	v_mul_f32_e32 v76, v18, v18
	v_mul_f32_e32 v77, v19, v19
	v_pk_add_f32 v[56:57], v[56:57], v[60:61]
	v_pk_add_f32 v[60:61], v[64:65], v[64:65] op_sel:[0,1] op_sel_hi:[1,0]
	v_pk_add_f32 v[30:31], v[30:31], v[30:31] op_sel:[0,1] op_sel_hi:[1,0]
	v_mov_b32_e32 v61, v77
	v_mov_b32_e32 v31, v76
	v_pk_add_f32 v[30:31], v[30:31], v[60:61]
	v_mul_f32_e32 v78, v6, v6
	v_pk_add_f32 v[30:31], v[30:31], v[54:55]
	v_mul_f32_e32 v79, v7, v7
	v_pk_add_f32 v[58:59], v[58:59], v[58:59] op_sel:[0,1] op_sel_hi:[1,0]
	v_pk_add_f32 v[30:31], v[30:31], v[30:31] op_sel:[0,1] op_sel_hi:[1,0]
	v_mov_b32_e32 v59, v79
	v_mov_b32_e32 v31, v78
	v_pk_add_f32 v[30:31], v[30:31], v[58:59]
	s_nop 0
	v_pk_add_f32 v[30:31], v[30:31], v[56:57]
	s_nop 0
	v_add_f32_e32 v30, v30, v31
	ds_bpermute_b32 v31, v48, v30
	s_waitcnt lgkmcnt(0)
	v_add_f32_e32 v30, v30, v31
	ds_bpermute_b32 v31, v49, v30
	s_waitcnt lgkmcnt(0)
	v_add_f32_e32 v30, v30, v31
	ds_bpermute_b32 v31, v50, v30
	s_waitcnt lgkmcnt(0)
; __device__ __forceinline__ unsigned pk2(float lo, float hi) { return f2bf(lo) | (f2bf(hi) << 16); }
; __device__ __forceinline__ float wave_sum(float v) {
; #pragma unroll
;     for (int o = 32; o >= 1; o >>= 1) v += __shfl_xor(v, o);
;     return v;
; }
; __device__ __forceinline__ void rms_row_to_bf16(const float* xrow, const float* gain, bf16* orow, int lane) {
;     ...
;     for (int j = 0; j < 8; ++j) { v[j] = xr[64 * j]; s += (v[j].x * v[j].x + v[j].y * v[j].y) + (v[j].z * v[j].z + v[j].w * v[j].w); }
;     const float r = 1.0f / sqrtf(wave_sum(s) * (1.0f / DM) + 1e-6f);
;     u32x2* o8 = (u32x2*)orow + lane;
; #pragma unroll
;     for (int j = 0; j < 8; ++j) { const f32x4 g = gr[64 * j]; u32x2 w; w.x = pk2(v[j].x * r * g.x, v[j].y * r * g.y); w.y = pk2(v[j].z * r * g.z, v[j].w * r * g.w); o8[64 * j] = w; }
	v_add_f32_e32 v30, v30, v31
	ds_bpermute_b32 v31, v51, v30
	s_waitcnt lgkmcnt(0)
	v_add_f32_e32 v30, v30, v31
	ds_bpermute_b32 v31, v52, v30
	s_waitcnt lgkmcnt(0)
	v_add_f32_e32 v30, v30, v31
	ds_bpermute_b32 v31, v53, v30
	s_waitcnt lgkmcnt(0)
	v_add_f32_e32 v30, v30, v31
	v_fmamk_f32 v30, v30, 0x3a000000, v221
	v_mul_f32_e32 v31, 0x4f800000, v30
	v_cmp_gt_f32_e32 vcc, s87, v30
	s_nop 1
	v_cndmask_b32_e32 v30, v30, v31, vcc
	v_sqrt_f32_e32 v31, v30
	s_nop 0
	v_add_u32_e32 v54, -1, v31
	v_add_u32_e32 v55, 1, v31
	v_fma_f32 v56, -v54, v31, v30
	v_fma_f32 v57, -v55, v31, v30
	v_cmp_ge_f32_e64 s[0:1], 0, v56
	s_nop 1
	v_cndmask_b32_e64 v31, v31, v54, s[0:1]
	v_cmp_lt_f32_e64 s[0:1], 0, v57
	s_nop 1
	v_cndmask_b32_e64 v31, v31, v55, s[0:1]
	v_mul_f32_e32 v54, 0x37800000, v31
	v_cndmask_b32_e32 v31, v31, v54, vcc
	v_cmp_class_f32_e32 vcc, v30, v222
	s_nop 1
	v_cndmask_b32_e32 v30, v31, v30, vcc
	v_div_scale_f32 v31, s[0:1], v30, v30, 1.0
	v_rcp_f32_e32 v55, v31
	v_div_scale_f32 v54, vcc, 1.0, v30, 1.0
	v_fma_f32 v56, -v31, v55, 1.0
	v_fmac_f32_e32 v55, v56, v55
	v_mul_f32_e32 v56, v54, v55
	v_fma_f32 v57, -v31, v56, v54
	v_fmac_f32_e32 v56, v57, v55
	v_fma_f32 v31, -v31, v56, v54
	v_div_fmas_f32 v31, v31, v55, v56
	v_div_fixup_f32 v30, v31, v30, 1.0
	v_pk_mul_f32 v[34:35], v[34:35], v[30:31] op_sel_hi:[1,0]
	v_pk_mul_f32 v[40:41], v[40:41], v[30:31] op_sel_hi:[1,0]
	v_pk_mul_f32 v[34:35], v[46:47], v[34:35]
	v_pk_mul_f32 v[36:37], v[36:37], v[40:41]
	v_pk_mul_f32 v[38:39], v[38:39], v[30:31] op_sel_hi:[1,0]
	v_and_b32_sdwa v31, v35, v225 dst_sel:DWORD dst_unused:UNUSED_PAD src0_sel:WORD_1 src1_sel:DWORD
	v_and_b32_sdwa v41, v37, v225 dst_sel:DWORD dst_unused:UNUSED_PAD src0_sel:WORD_1 src1_sel:DWORD
	v_and_b32_sdwa v46, v36, v225 dst_sel:DWORD dst_unused:UNUSED_PAD src0_sel:WORD_1 src1_sel:DWORD
	v_and_b32_sdwa v40, v34, v225 dst_sel:DWORD dst_unused:UNUSED_PAD src0_sel:WORD_1 src1_sel:DWORD
	v_add3_u32 v31, v35, v31, s72
	v_add3_u32 v35, v37, v41, s72
	v_add3_u32 v36, v36, v46, s72
	v_add3_u32 v34, v34, v40, s72
	v_and_b32_e32 v35, 0xffff0000, v35
	v_and_b32_e32 v36, 0xffff0000, v36
	v_or_b32_sdwa v35, v35, v31 dst_sel:DWORD dst_unused:UNUSED_PAD src0_sel:DWORD src1_sel:WORD_1
	v_or_b32_sdwa v34, v36, v34 dst_sel:DWORD dst_unused:UNUSED_PAD src0_sel:DWORD src1_sel:WORD_1
	global_store_dwordx2 v[44:45], v[34:35], off offset:-2048
	s_nop 1
	v_mov_b64_e32 v[34:35], v[84:85]
	v_mov_b64_e32 v[36:37], v[86:87]
	v_pk_mul_f32 v[32:33], v[32:33], v[30:31] op_sel_hi:[1,0]
	v_mov_b32_e32 v41, v36
	v_mov_b32_e32 v36, v35
	v_mov_b32_e32 v40, v34
	v_pk_mul_f32 v[32:33], v[36:37], v[32:33]
	v_pk_mul_f32 v[34:35], v[40:41], v[38:39]
	v_and_b32_sdwa v37, v33, v225 dst_sel:DWORD dst_unused:UNUSED_PAD src0_sel:WORD_1 src1_sel:DWORD
	v_and_b32_sdwa v38, v32, v225 dst_sel:DWORD dst_unused:UNUSED_PAD src0_sel:WORD_1 src1_sel:DWORD
	v_and_b32_sdwa v31, v35, v225 dst_sel:DWORD dst_unused:UNUSED_PAD src0_sel:WORD_1 src1_sel:DWORD
	v_and_b32_sdwa v36, v34, v225 dst_sel:DWORD dst_unused:UNUSED_PAD src0_sel:WORD_1 src1_sel:DWORD
	v_add3_u32 v33, v33, v37, s72
	v_add3_u32 v32, v32, v38, s72
	v_add3_u32 v34, v34, v36, s72
	v_add3_u32 v31, v35, v31, s72
	v_and_b32_e32 v33, 0xffff0000, v33
	v_and_b32_e32 v32, 0xffff0000, v32
	v_or_b32_sdwa v33, v33, v31 dst_sel:DWORD dst_unused:UNUSED_PAD src0_sel:DWORD src1_sel:WORD_1
	v_or_b32_sdwa v32, v32, v34 dst_sel:DWORD dst_unused:UNUSED_PAD src0_sel:DWORD src1_sel:WORD_1
	global_store_dwordx2 v[44:45], v[32:33], off offset:-1536
	s_nop 1
	v_mov_b64_e32 v[32:33], v[88:89]
	v_mov_b64_e32 v[34:35], v[90:91]
	v_mov_b32_e32 v36, v26
	v_mov_b32_e32 v37, v28
	v_mov_b32_e32 v28, v27
	v_pk_mul_f32 v[26:27], v[36:37], v[30:31] op_sel_hi:[1,0]
	v_pk_mul_f32 v[28:29], v[28:29], v[30:31] op_sel_hi:[1,0]
	v_mov_b32_e32 v37, v34
	v_mov_b32_e32 v34, v33
	v_mov_b32_e32 v36, v32
	v_pk_mul_f32 v[28:29], v[34:35], v[28:29]
	v_pk_mul_f32 v[26:27], v[36:37], v[26:27]
	v_and_b32_sdwa v33, v29, v225 dst_sel:DWORD dst_unused:UNUSED_PAD src0_sel:WORD_1 src1_sel:DWORD
	v_and_b32_sdwa v34, v28, v225 dst_sel:DWORD dst_unused:UNUSED_PAD src0_sel:WORD_1 src1_sel:DWORD
	v_and_b32_sdwa v31, v27, v225 dst_sel:DWORD dst_unused:UNUSED_PAD src0_sel:WORD_1 src1_sel:DWORD
	v_and_b32_sdwa v32, v26, v225 dst_sel:DWORD dst_unused:UNUSED_PAD src0_sel:WORD_1 src1_sel:DWORD
	v_add3_u32 v29, v29, v33, s72
	v_add3_u32 v28, v28, v34, s72
	v_add3_u32 v26, v26, v32, s72
	v_add3_u32 v27, v27, v31, s72
	v_and_b32_e32 v29, 0xffff0000, v29
	v_and_b32_e32 v28, 0xffff0000, v28
	v_or_b32_sdwa v27, v29, v27 dst_sel:DWORD dst_unused:UNUSED_PAD src0_sel:DWORD src1_sel:WORD_1
	v_or_b32_sdwa v26, v28, v26 dst_sel:DWORD dst_unused:UNUSED_PAD src0_sel:DWORD src1_sel:WORD_1
	global_store_dwordx2 v[44:45], v[26:27], off offset:-1024
	s_nop 1
	v_mov_b64_e32 v[32:33], v[92:93]
	v_mov_b64_e32 v[34:35], v[94:95]
	v_mov_b32_e32 v28, v22
	v_mov_b32_e32 v29, v24
	v_mov_b32_e32 v24, v23
	v_pk_mul_f32 v[22:23], v[28:29], v[30:31] op_sel_hi:[1,0]
	v_pk_mul_f32 v[24:25], v[24:25], v[30:31] op_sel_hi:[1,0]
	v_lshl_add_u64 v[26:27], s[4:5], 0, v[0:1]
	v_add_co_u32_e32 v26, vcc, s70, v26
	v_mov_b32_e32 v29, v34
	v_mov_b32_e32 v34, v33
	v_mov_b32_e32 v28, v32
	v_pk_mul_f32 v[24:25], v[34:35], v[24:25]
	v_pk_mul_f32 v[22:23], v[28:29], v[22:23]
	v_and_b32_sdwa v31, v25, v225 dst_sel:DWORD dst_unused:UNUSED_PAD src0_sel:WORD_1 src1_sel:DWORD
	v_and_b32_sdwa v32, v24, v225 dst_sel:DWORD dst_unused:UNUSED_PAD src0_sel:WORD_1 src1_sel:DWORD
	v_and_b32_sdwa v28, v23, v225 dst_sel:DWORD dst_unused:UNUSED_PAD src0_sel:WORD_1 src1_sel:DWORD
	v_and_b32_sdwa v29, v22, v225 dst_sel:DWORD dst_unused:UNUSED_PAD src0_sel:WORD_1 src1_sel:DWORD
; __device__ __forceinline__ unsigned pk2(float lo, float hi) { return f2bf(lo) | (f2bf(hi) << 16); }
; __device__ __forceinline__ void rms_row_to_bf16(const float* xrow, const float* gain, bf16* orow, int lane) {
;     ...
;     u32x2* o8 = (u32x2*)orow + lane;
; #pragma unroll
;     for (int j = 0; j < 8; ++j) { const f32x4 g = gr[64 * j]; u32x2 w; w.x = pk2(v[j].x * r * g.x, v[j].y * r * g.y); w.y = pk2(v[j].z * r * g.z, v[j].w * r * g.w); o8[64 * j] = w; }
	v_add3_u32 v25, v25, v31, s72
	v_add3_u32 v24, v24, v32, s72
	v_add3_u32 v22, v22, v29, s72
	v_add3_u32 v23, v23, v28, s72
	v_and_b32_e32 v25, 0xffff0000, v25
	v_and_b32_e32 v24, 0xffff0000, v24
	v_or_b32_sdwa v23, v25, v23 dst_sel:DWORD dst_unused:UNUSED_PAD src0_sel:DWORD src1_sel:WORD_1
	v_or_b32_sdwa v22, v24, v22 dst_sel:DWORD dst_unused:UNUSED_PAD src0_sel:DWORD src1_sel:WORD_1
	v_addc_co_u32_e32 v27, vcc, 0, v27, vcc
	global_store_dwordx2 v[44:45], v[22:23], off offset:-512
	s_nop 1
	v_mov_b64_e32 v[22:23], v[96:97]
	v_mov_b64_e32 v[24:25], v[98:99]
	v_mov_b32_e32 v28, v18
	v_mov_b32_e32 v29, v20
	v_mov_b32_e32 v20, v19
	v_pk_mul_f32 v[18:19], v[28:29], v[30:31] op_sel_hi:[1,0]
	v_pk_mul_f32 v[20:21], v[20:21], v[30:31] op_sel_hi:[1,0]
	v_mov_b32_e32 v29, v24
	v_mov_b32_e32 v24, v23
	v_mov_b32_e32 v28, v22
	v_pk_mul_f32 v[20:21], v[20:21], v[24:25]
	v_pk_mul_f32 v[18:19], v[18:19], v[28:29]
	v_and_b32_sdwa v24, v21, v225 dst_sel:DWORD dst_unused:UNUSED_PAD src0_sel:WORD_1 src1_sel:DWORD
	v_and_b32_sdwa v25, v20, v225 dst_sel:DWORD dst_unused:UNUSED_PAD src0_sel:WORD_1 src1_sel:DWORD
	v_and_b32_sdwa v22, v19, v225 dst_sel:DWORD dst_unused:UNUSED_PAD src0_sel:WORD_1 src1_sel:DWORD
	v_and_b32_sdwa v23, v18, v225 dst_sel:DWORD dst_unused:UNUSED_PAD src0_sel:WORD_1 src1_sel:DWORD
	v_add3_u32 v21, v21, v24, s72
	v_add3_u32 v20, v20, v25, s72
	v_add3_u32 v18, v18, v23, s72
	v_add3_u32 v19, v19, v22, s72
	v_and_b32_e32 v21, 0xffff0000, v21
	v_and_b32_e32 v20, 0xffff0000, v20
	v_or_b32_sdwa v19, v21, v19 dst_sel:DWORD dst_unused:UNUSED_PAD src0_sel:DWORD src1_sel:WORD_1
	v_or_b32_sdwa v18, v20, v18 dst_sel:DWORD dst_unused:UNUSED_PAD src0_sel:DWORD src1_sel:WORD_1
	global_store_dwordx2 v[44:45], v[18:19], off
	s_nop 1
	v_mov_b64_e32 v[18:19], v[100:101]
	v_mov_b64_e32 v[20:21], v[102:103]
	v_mov_b32_e32 v22, v14
	v_mov_b32_e32 v23, v16
	v_mov_b32_e32 v16, v15
	v_pk_mul_f32 v[14:15], v[22:23], v[30:31] op_sel_hi:[1,0]
	v_pk_mul_f32 v[16:17], v[16:17], v[30:31] op_sel_hi:[1,0]
	v_mov_b32_e32 v23, v20
	v_mov_b32_e32 v20, v19
	v_mov_b32_e32 v22, v18
	v_pk_mul_f32 v[16:17], v[16:17], v[20:21]
	v_pk_mul_f32 v[14:15], v[14:15], v[22:23]
	v_and_b32_sdwa v20, v17, v225 dst_sel:DWORD dst_unused:UNUSED_PAD src0_sel:WORD_1 src1_sel:DWORD
	v_and_b32_sdwa v21, v16, v225 dst_sel:DWORD dst_unused:UNUSED_PAD src0_sel:WORD_1 src1_sel:DWORD
	v_and_b32_sdwa v18, v15, v225 dst_sel:DWORD dst_unused:UNUSED_PAD src0_sel:WORD_1 src1_sel:DWORD
	v_and_b32_sdwa v19, v14, v225 dst_sel:DWORD dst_unused:UNUSED_PAD src0_sel:WORD_1 src1_sel:DWORD
	v_add3_u32 v17, v17, v20, s72
	v_add3_u32 v16, v16, v21, s72
	v_add3_u32 v14, v14, v19, s72
	v_add3_u32 v15, v15, v18, s72
	v_and_b32_e32 v17, 0xffff0000, v17
	v_and_b32_e32 v16, 0xffff0000, v16
	v_or_b32_sdwa v15, v17, v15 dst_sel:DWORD dst_unused:UNUSED_PAD src0_sel:DWORD src1_sel:WORD_1
	v_or_b32_sdwa v14, v16, v14 dst_sel:DWORD dst_unused:UNUSED_PAD src0_sel:DWORD src1_sel:WORD_1
	global_store_dwordx2 v[44:45], v[14:15], off offset:512
	s_nop 1
	v_mov_b64_e32 v[14:15], v[104:105]
	v_mov_b64_e32 v[16:17], v[106:107]
	v_mov_b32_e32 v18, v10
	v_mov_b32_e32 v19, v12
	v_mov_b32_e32 v12, v11
	v_pk_mul_f32 v[10:11], v[18:19], v[30:31] op_sel_hi:[1,0]
	v_pk_mul_f32 v[12:13], v[12:13], v[30:31] op_sel_hi:[1,0]
	v_mov_b32_e32 v19, v16
	v_mov_b32_e32 v16, v15
	v_mov_b32_e32 v18, v14
	v_pk_mul_f32 v[12:13], v[12:13], v[16:17]
	v_pk_mul_f32 v[10:11], v[10:11], v[18:19]
	v_and_b32_sdwa v16, v13, v225 dst_sel:DWORD dst_unused:UNUSED_PAD src0_sel:WORD_1 src1_sel:DWORD
	v_and_b32_sdwa v17, v12, v225 dst_sel:DWORD dst_unused:UNUSED_PAD src0_sel:WORD_1 src1_sel:DWORD
	v_and_b32_sdwa v14, v11, v225 dst_sel:DWORD dst_unused:UNUSED_PAD src0_sel:WORD_1 src1_sel:DWORD
	v_and_b32_sdwa v15, v10, v225 dst_sel:DWORD dst_unused:UNUSED_PAD src0_sel:WORD_1 src1_sel:DWORD
	v_add3_u32 v13, v13, v16, s72
	v_add3_u32 v12, v12, v17, s72
	v_add3_u32 v10, v10, v15, s72
	v_add3_u32 v11, v11, v14, s72
	v_and_b32_e32 v13, 0xffff0000, v13
	v_and_b32_e32 v12, 0xffff0000, v12
	v_or_b32_sdwa v11, v13, v11 dst_sel:DWORD dst_unused:UNUSED_PAD src0_sel:DWORD src1_sel:WORD_1
	v_or_b32_sdwa v10, v12, v10 dst_sel:DWORD dst_unused:UNUSED_PAD src0_sel:DWORD src1_sel:WORD_1
	global_store_dwordx2 v[44:45], v[10:11], off offset:1024
	s_nop 1
	v_mov_b64_e32 v[10:11], v[108:109]
	v_mov_b64_e32 v[12:13], v[110:111]
	v_mov_b32_e32 v14, v6
	v_mov_b32_e32 v15, v8
	v_mov_b32_e32 v8, v7
	v_pk_mul_f32 v[6:7], v[14:15], v[30:31] op_sel_hi:[1,0]
	v_pk_mul_f32 v[8:9], v[8:9], v[30:31] op_sel_hi:[1,0]
	v_mov_b32_e32 v15, v12
	v_mov_b32_e32 v12, v11
	v_mov_b32_e32 v14, v10
	v_pk_mul_f32 v[8:9], v[8:9], v[12:13]
	v_pk_mul_f32 v[6:7], v[6:7], v[14:15]
	v_and_b32_sdwa v12, v9, v225 dst_sel:DWORD dst_unused:UNUSED_PAD src0_sel:WORD_1 src1_sel:DWORD
	v_and_b32_sdwa v13, v8, v225 dst_sel:DWORD dst_unused:UNUSED_PAD src0_sel:WORD_1 src1_sel:DWORD
	v_and_b32_sdwa v10, v7, v225 dst_sel:DWORD dst_unused:UNUSED_PAD src0_sel:WORD_1 src1_sel:DWORD
	v_and_b32_sdwa v11, v6, v225 dst_sel:DWORD dst_unused:UNUSED_PAD src0_sel:WORD_1 src1_sel:DWORD
	v_add3_u32 v9, v9, v12, s72
	v_add3_u32 v8, v8, v13, s72
	v_add3_u32 v6, v6, v11, s72
	v_add3_u32 v7, v7, v10, s72
	v_and_b32_e32 v9, 0xffff0000, v9
	v_and_b32_e32 v8, 0xffff0000, v8
	v_or_b32_sdwa v7, v9, v7 dst_sel:DWORD dst_unused:UNUSED_PAD src0_sel:DWORD src1_sel:WORD_1
	v_or_b32_sdwa v6, v8, v6 dst_sel:DWORD dst_unused:UNUSED_PAD src0_sel:DWORD src1_sel:WORD_1
	global_store_dwordx2 v[44:45], v[6:7], off offset:1536
	v_lshl_add_u64 v[44:45], v[44:45], 0, s[6:7]
	s_cbranch_scc0 .LBB0_513
